# v40 with s_sleep removed from the grid-barrier poll loops (12 sites)
# baseline (speedup 1.0000x reference)
.LXB2_SPIN_0:
	global_load_dword v3, v5, s[14:15] sc1
	s_waitcnt vmcnt(0)
	v_readfirstlane_b32 s9, v3
	s_cmp_ge_u32 s9, s8
	s_cbranch_scc1 .LXB2_ACQ_0
	s_add_i32 s16, s16, 1
	s_cmp_lt_u32 s16, 0x200000
	s_cbranch_scc1 .LXB2_SPIN_0
